# gate/up GEMM: first K-iteration peeled with zero SrcC on first-touch MFMAs, per-tile accumulator zeroing removed
# speedup vs baseline: 1.0111x; 1.0111x over previous
.LBB0_401:
	v_mov_b64_e32 v[0:1], 0x580
	s_ashr_i32 s9, s8, 31
	v_cmp_lt_i64_e32 vcc, s[12:13], v[0:1]
	s_lshl_b64 s[12:13], s[8:9], 19
	v_readlane_b32 s14, v254, 33
	v_readlane_b32 s15, v254, 34
	s_add_u32 s12, s14, s12
	s_addc_u32 s13, s15, s13
	s_and_b64 s[14:15], vcc, exec
	s_cselect_b32 s1, s13, s21
	s_cselect_b32 s9, s12, s20
	s_ashr_i32 s11, s10, 31
	s_lshl_b64 s[14:15], s[10:11], 19
	s_add_u32 s14, s26, s14
	s_addc_u32 s15, s27, s15
	s_and_b64 s[22:23], vcc, exec
	s_cselect_b32 s11, s15, s19
	s_cselect_b32 s33, s14, s18
	s_add_u32 s38, s18, 0x100
	s_addc_u32 s39, s19, 0
	s_add_u32 s18, s20, 0x40080
	s_addc_u32 s19, s21, 0
	s_mov_b32 s40, -2
	s_waitcnt vmcnt(0)
	v_add_u32_e32 v218, 0x10000, v145
	v_add_u32_e32 v219, 0x14000, v145
	v_add_u32_e32 v220, 0x18000, v145
	v_add_u32_e32 v221, 0x1c000, v145
	s_add_u32 s20, s18, 0xfffc0080
	s_addc_u32 s21, s19, -1
	s_add_i32 s41, 0, 0x10000
	ds_read_b128 v[138:141], v218
	ds_read_b128 v[148:151], v218 offset:1024
	ds_read_b128 v[152:155], v218 offset:2048
	ds_read_b128 v[156:159], v218 offset:3072
	s_cmp_eq_u32 s40, 12
	s_cselect_b32 s23, s1, s21
	s_cselect_b32 s22, s9, s20
	s_cselect_b32 s21, s11, s39
	s_cselect_b32 s20, s33, s38
	s_add_i32 m0, s17, 0xc000
	ds_read_b128 v[160:163], v146
	ds_read_b128 v[164:167], v146 offset:1024
	ds_read_b128 v[168:171], v146 offset:2048
	ds_read_b128 v[172:175], v146 offset:3072
	ds_read_b128 v[176:179], v146 offset:4096
	ds_read_b128 v[180:183], v146 offset:5120
	ds_read_b128 v[184:187], v146 offset:6144
	ds_read_b128 v[188:191], v146 offset:7168
	global_load_lds_dwordx4 v136, s[18:19]
	s_add_i32 m0, s17, 0xe000
	s_nop 0
	global_load_lds_dwordx4 v134, s[18:19]
	s_waitcnt lgkmcnt(8)
	s_barrier
	s_waitcnt lgkmcnt(0)
	v_mfma_f32_16x16x32_bf16 v[124:127], v[138:141], v[160:163], 0
	v_mfma_f32_16x16x32_bf16 v[116:119], v[152:155], v[160:163], 0
	v_mfma_f32_16x16x32_bf16 v[108:111], v[138:141], v[168:171], 0
	v_mfma_f32_16x16x32_bf16 v[100:103], v[152:155], v[168:171], 0
	v_mfma_f32_16x16x32_bf16 v[92:95], v[138:141], v[176:179], 0
	v_mfma_f32_16x16x32_bf16 v[84:87], v[152:155], v[176:179], 0
	v_mfma_f32_16x16x32_bf16 v[76:79], v[138:141], v[184:187], 0
	v_mfma_f32_16x16x32_bf16 v[68:71], v[152:155], v[184:187], 0
	v_mfma_f32_16x16x32_bf16 v[124:127], v[148:151], v[164:167], v[124:127]
	v_mfma_f32_16x16x32_bf16 v[116:119], v[156:159], v[164:167], v[116:119]
	v_mfma_f32_16x16x32_bf16 v[108:111], v[148:151], v[172:175], v[108:111]
	v_mfma_f32_16x16x32_bf16 v[100:103], v[156:159], v[172:175], v[100:103]
	v_mfma_f32_16x16x32_bf16 v[92:95], v[148:151], v[180:183], v[92:95]
	v_mfma_f32_16x16x32_bf16 v[84:87], v[156:159], v[180:183], v[84:87]
	v_mfma_f32_16x16x32_bf16 v[76:79], v[148:151], v[188:191], v[76:79]
	v_mfma_f32_16x16x32_bf16 v[68:71], v[156:159], v[188:191], v[68:71]
	s_barrier
	s_add_i32 s44, 0, 0x14000
	s_add_i32 s41, s41, s28
	ds_read_b128 v[198:201], v219
	ds_read_b128 v[206:209], v219 offset:1024
	ds_read_b128 v[210:213], v219 offset:2048
	ds_read_b128 v[214:217], v219 offset:3072
	s_mov_b32 m0, s41
	s_nop 0
	global_load_lds_dwordx4 v192, s[20:21]
	s_add_i32 m0, s41, 0x2000
	s_nop 0
	global_load_lds_dwordx4 v128, s[20:21]
	s_barrier
	s_waitcnt lgkmcnt(0)
	v_mfma_f32_16x16x32_bf16 v[120:123], v[198:201], v[160:163], 0
	v_mfma_f32_16x16x32_bf16 v[112:115], v[210:213], v[160:163], 0
	v_mfma_f32_16x16x32_bf16 v[104:107], v[198:201], v[168:171], 0
	v_mfma_f32_16x16x32_bf16 v[96:99], v[210:213], v[168:171], 0
	v_mfma_f32_16x16x32_bf16 v[88:91], v[198:201], v[176:179], 0
	v_mfma_f32_16x16x32_bf16 v[80:83], v[210:213], v[176:179], 0
	v_mfma_f32_16x16x32_bf16 v[72:75], v[198:201], v[184:187], 0
	v_mfma_f32_16x16x32_bf16 v[64:67], v[210:213], v[184:187], 0
	v_mfma_f32_16x16x32_bf16 v[120:123], v[206:209], v[164:167], v[120:123]
	v_mfma_f32_16x16x32_bf16 v[112:115], v[214:217], v[164:167], v[112:115]
	v_mfma_f32_16x16x32_bf16 v[104:107], v[206:209], v[172:175], v[104:107]
	v_mfma_f32_16x16x32_bf16 v[96:99], v[214:217], v[172:175], v[96:99]
	v_mfma_f32_16x16x32_bf16 v[88:91], v[206:209], v[180:183], v[88:91]
	v_mfma_f32_16x16x32_bf16 v[80:83], v[214:217], v[180:183], v[80:83]
	v_mfma_f32_16x16x32_bf16 v[72:75], v[206:209], v[188:191], v[72:75]
	v_mfma_f32_16x16x32_bf16 v[64:67], v[214:217], v[188:191], v[64:67]
	s_mov_b32 m0, s17
	s_add_u32 vcc_lo, s22, 0x80
	s_addc_u32 vcc_hi, s23, 0
	s_barrier
	ds_read_b128 v[160:163], v146 offset:16384
	ds_read_b128 v[164:167], v146 offset:17408
	ds_read_b128 v[168:171], v146 offset:18432
	ds_read_b128 v[172:175], v146 offset:19456
	ds_read_b128 v[176:179], v146 offset:20480
	ds_read_b128 v[180:183], v146 offset:21504
	ds_read_b128 v[184:187], v146 offset:22528
	ds_read_b128 v[188:191], v146 offset:23552
	global_load_lds_dwordx4 v132, s[22:23]
	s_mov_b32 m0, s29
	s_nop 0
	global_load_lds_dwordx4 v130, s[22:23]
	s_barrier
	s_waitcnt lgkmcnt(0)
	v_mfma_f32_16x16x32_bf16 v[60:63], v[138:141], v[160:163], 0
	v_mfma_f32_16x16x32_bf16 v[52:55], v[152:155], v[160:163], 0
	v_mfma_f32_16x16x32_bf16 v[44:47], v[138:141], v[168:171], 0
	v_mfma_f32_16x16x32_bf16 v[36:39], v[152:155], v[168:171], 0
	v_mfma_f32_16x16x32_bf16 v[28:31], v[138:141], v[176:179], 0
	v_mfma_f32_16x16x32_bf16 v[20:23], v[152:155], v[176:179], 0
	v_mfma_f32_16x16x32_bf16 v[12:15], v[138:141], v[184:187], 0
	v_mfma_f32_16x16x32_bf16 v[4:7], v[152:155], v[184:187], 0
	v_mfma_f32_16x16x32_bf16 v[60:63], v[148:151], v[164:167], v[60:63]
	v_mfma_f32_16x16x32_bf16 v[52:55], v[156:159], v[164:167], v[52:55]
	v_mfma_f32_16x16x32_bf16 v[44:47], v[148:151], v[172:175], v[44:47]
	v_mfma_f32_16x16x32_bf16 v[36:39], v[156:159], v[172:175], v[36:39]
	v_mfma_f32_16x16x32_bf16 v[28:31], v[148:151], v[180:183], v[28:31]
	v_mfma_f32_16x16x32_bf16 v[20:23], v[156:159], v[180:183], v[20:23]
	v_mfma_f32_16x16x32_bf16 v[12:15], v[148:151], v[188:191], v[12:15]
	v_mfma_f32_16x16x32_bf16 v[4:7], v[156:159], v[188:191], v[4:7]
	s_barrier
	s_add_u32 s42, s20, 0x40000
	s_addc_u32 s43, s21, 0
	s_add_i32 s41, s44, s28
	s_mov_b32 m0, s41
	s_nop 0
	global_load_lds_dwordx4 v192, s[42:43]
	s_add_i32 m0, s41, 0x2000
	s_nop 0
	global_load_lds_dwordx4 v128, s[42:43]
	s_waitcnt vmcnt(6)
	s_barrier
	v_mfma_f32_16x16x32_bf16 v[56:59], v[198:201], v[160:163], 0
	v_mfma_f32_16x16x32_bf16 v[48:51], v[210:213], v[160:163], 0
	v_mfma_f32_16x16x32_bf16 v[40:43], v[198:201], v[168:171], 0
	v_mfma_f32_16x16x32_bf16 v[32:35], v[210:213], v[168:171], 0
	v_mfma_f32_16x16x32_bf16 v[24:27], v[198:201], v[176:179], 0
	v_mfma_f32_16x16x32_bf16 v[16:19], v[210:213], v[176:179], 0
	v_mfma_f32_16x16x32_bf16 v[8:11], v[198:201], v[184:187], 0
	v_mfma_f32_16x16x32_bf16 v[0:3], v[210:213], v[184:187], 0
	v_mfma_f32_16x16x32_bf16 v[56:59], v[206:209], v[164:167], v[56:59]
	v_mfma_f32_16x16x32_bf16 v[48:51], v[214:217], v[164:167], v[48:51]
	v_mfma_f32_16x16x32_bf16 v[40:43], v[206:209], v[172:175], v[40:43]
	v_mfma_f32_16x16x32_bf16 v[32:35], v[214:217], v[172:175], v[32:35]
	v_mfma_f32_16x16x32_bf16 v[24:27], v[206:209], v[180:183], v[24:27]
	v_mfma_f32_16x16x32_bf16 v[16:19], v[214:217], v[180:183], v[16:19]
	v_mfma_f32_16x16x32_bf16 v[8:11], v[206:209], v[188:191], v[8:11]
	v_mfma_f32_16x16x32_bf16 v[0:3], v[214:217], v[188:191], v[0:3]
	s_add_i32 s41, 0, 0x18000
	s_barrier
	ds_read_b128 v[138:141], v220
	ds_read_b128 v[148:151], v220 offset:1024
	ds_read_b128 v[152:155], v220 offset:2048
	ds_read_b128 v[156:159], v220 offset:3072
	s_add_u32 s22, s22, 0x40000
	s_addc_u32 s23, s23, 0
	s_mov_b32 m0, s30
	ds_read_b128 v[160:163], v146 offset:32768
	ds_read_b128 v[164:167], v146 offset:33792
	ds_read_b128 v[168:171], v146 offset:34816
	ds_read_b128 v[172:175], v146 offset:35840
	ds_read_b128 v[176:179], v146 offset:36864
	ds_read_b128 v[180:183], v146 offset:37888
	ds_read_b128 v[184:187], v146 offset:38912
	ds_read_b128 v[188:191], v146 offset:39936
	global_load_lds_dwordx4 v132, s[22:23]
	s_mov_b32 m0, s31
	s_nop 0
	global_load_lds_dwordx4 v130, s[22:23]
	s_waitcnt lgkmcnt(8)
	s_barrier
	s_waitcnt lgkmcnt(0)
	v_mfma_f32_16x16x32_bf16 v[124:127], v[138:141], v[160:163], v[124:127]
	v_mfma_f32_16x16x32_bf16 v[116:119], v[152:155], v[160:163], v[116:119]
	v_mfma_f32_16x16x32_bf16 v[108:111], v[138:141], v[168:171], v[108:111]
	v_mfma_f32_16x16x32_bf16 v[100:103], v[152:155], v[168:171], v[100:103]
	v_mfma_f32_16x16x32_bf16 v[92:95], v[138:141], v[176:179], v[92:95]
	v_mfma_f32_16x16x32_bf16 v[84:87], v[152:155], v[176:179], v[84:87]
	v_mfma_f32_16x16x32_bf16 v[76:79], v[138:141], v[184:187], v[76:79]
	v_mfma_f32_16x16x32_bf16 v[68:71], v[152:155], v[184:187], v[68:71]
	v_mfma_f32_16x16x32_bf16 v[124:127], v[148:151], v[164:167], v[124:127]
	v_mfma_f32_16x16x32_bf16 v[116:119], v[156:159], v[164:167], v[116:119]
	v_mfma_f32_16x16x32_bf16 v[108:111], v[148:151], v[172:175], v[108:111]
	v_mfma_f32_16x16x32_bf16 v[100:103], v[156:159], v[172:175], v[100:103]
	v_mfma_f32_16x16x32_bf16 v[92:95], v[148:151], v[180:183], v[92:95]
	v_mfma_f32_16x16x32_bf16 v[84:87], v[156:159], v[180:183], v[84:87]
	v_mfma_f32_16x16x32_bf16 v[76:79], v[148:151], v[188:191], v[76:79]
	v_mfma_f32_16x16x32_bf16 v[68:71], v[156:159], v[188:191], v[68:71]
	s_barrier
	s_add_i32 s22, 0, 0x1c000
	s_add_i32 s23, s41, s28
	s_add_u32 s100, s20, 0x80
	s_addc_u32 s101, s21, 0
	s_mov_b32 m0, s23
	ds_read_b128 v[198:201], v221
	ds_read_b128 v[206:209], v221 offset:1024
	ds_read_b128 v[210:213], v221 offset:2048
	ds_read_b128 v[214:217], v221 offset:3072
	global_load_lds_dwordx4 v192, s[100:101]
	s_add_i32 m0, s23, 0x2000
	s_nop 0
	global_load_lds_dwordx4 v128, s[100:101]
	s_barrier
	s_waitcnt lgkmcnt(0)
	v_mfma_f32_16x16x32_bf16 v[120:123], v[198:201], v[160:163], v[120:123]
	v_mfma_f32_16x16x32_bf16 v[112:115], v[210:213], v[160:163], v[112:115]
	v_mfma_f32_16x16x32_bf16 v[104:107], v[198:201], v[168:171], v[104:107]
	v_mfma_f32_16x16x32_bf16 v[96:99], v[210:213], v[168:171], v[96:99]
	v_mfma_f32_16x16x32_bf16 v[88:91], v[198:201], v[176:179], v[88:91]
	v_mfma_f32_16x16x32_bf16 v[80:83], v[210:213], v[176:179], v[80:83]
	v_mfma_f32_16x16x32_bf16 v[72:75], v[198:201], v[184:187], v[72:75]
	v_mfma_f32_16x16x32_bf16 v[64:67], v[210:213], v[184:187], v[64:67]
	v_mfma_f32_16x16x32_bf16 v[120:123], v[206:209], v[164:167], v[120:123]
	v_mfma_f32_16x16x32_bf16 v[112:115], v[214:217], v[164:167], v[112:115]
	v_mfma_f32_16x16x32_bf16 v[104:107], v[206:209], v[172:175], v[104:107]
	v_mfma_f32_16x16x32_bf16 v[96:99], v[214:217], v[172:175], v[96:99]
	v_mfma_f32_16x16x32_bf16 v[88:91], v[206:209], v[180:183], v[88:91]
	v_mfma_f32_16x16x32_bf16 v[80:83], v[214:217], v[180:183], v[80:83]
	v_mfma_f32_16x16x32_bf16 v[72:75], v[206:209], v[188:191], v[72:75]
	v_mfma_f32_16x16x32_bf16 v[64:67], v[214:217], v[188:191], v[64:67]
	s_mov_b32 m0, s34
	s_barrier
	ds_read_b128 v[160:163], v146 offset:49152
	ds_read_b128 v[164:167], v146 offset:50176
	ds_read_b128 v[168:171], v146 offset:51200
	ds_read_b128 v[172:175], v146 offset:52224
	ds_read_b128 v[176:179], v146 offset:53248
	ds_read_b128 v[180:183], v146 offset:54272
	ds_read_b128 v[184:187], v146 offset:55296
	ds_read_b128 v[188:191], v146 offset:56320
	global_load_lds_dwordx4 v132, vcc
	s_mov_b32 m0, s35
	s_nop 0
	global_load_lds_dwordx4 v130, vcc
	s_barrier
	s_waitcnt lgkmcnt(0)
	v_mfma_f32_16x16x32_bf16 v[60:63], v[138:141], v[160:163], v[60:63]
	v_mfma_f32_16x16x32_bf16 v[52:55], v[152:155], v[160:163], v[52:55]
	v_mfma_f32_16x16x32_bf16 v[44:47], v[138:141], v[168:171], v[44:47]
	v_mfma_f32_16x16x32_bf16 v[36:39], v[152:155], v[168:171], v[36:39]
	v_mfma_f32_16x16x32_bf16 v[28:31], v[138:141], v[176:179], v[28:31]
	v_mfma_f32_16x16x32_bf16 v[20:23], v[152:155], v[176:179], v[20:23]
	v_mfma_f32_16x16x32_bf16 v[12:15], v[138:141], v[184:187], v[12:15]
	v_mfma_f32_16x16x32_bf16 v[4:7], v[152:155], v[184:187], v[4:7]
	v_mfma_f32_16x16x32_bf16 v[60:63], v[148:151], v[164:167], v[60:63]
	v_mfma_f32_16x16x32_bf16 v[52:55], v[156:159], v[164:167], v[52:55]
	v_mfma_f32_16x16x32_bf16 v[44:47], v[148:151], v[172:175], v[44:47]
	v_mfma_f32_16x16x32_bf16 v[36:39], v[156:159], v[172:175], v[36:39]
	v_mfma_f32_16x16x32_bf16 v[28:31], v[148:151], v[180:183], v[28:31]
	v_mfma_f32_16x16x32_bf16 v[20:23], v[156:159], v[180:183], v[20:23]
	v_mfma_f32_16x16x32_bf16 v[12:15], v[148:151], v[188:191], v[12:15]
	v_mfma_f32_16x16x32_bf16 v[4:7], v[156:159], v[188:191], v[4:7]
	s_barrier
	s_add_u32 s20, s20, 0x40080
	s_addc_u32 s21, s21, 0
	s_add_i32 s22, s22, s28
	s_mov_b32 m0, s22
	s_nop 0
	global_load_lds_dwordx4 v192, s[20:21]
	s_add_i32 m0, s22, 0x2000
	s_nop 0
	global_load_lds_dwordx4 v128, s[20:21]
	s_waitcnt vmcnt(6)
	s_barrier
	v_mfma_f32_16x16x32_bf16 v[56:59], v[198:201], v[160:163], v[56:59]
	v_mfma_f32_16x16x32_bf16 v[48:51], v[210:213], v[160:163], v[48:51]
	v_mfma_f32_16x16x32_bf16 v[40:43], v[198:201], v[168:171], v[40:43]
	v_mfma_f32_16x16x32_bf16 v[32:35], v[210:213], v[168:171], v[32:35]
	v_mfma_f32_16x16x32_bf16 v[24:27], v[198:201], v[176:179], v[24:27]
	v_mfma_f32_16x16x32_bf16 v[16:19], v[210:213], v[176:179], v[16:19]
	v_mfma_f32_16x16x32_bf16 v[8:11], v[198:201], v[184:187], v[8:11]
	v_mfma_f32_16x16x32_bf16 v[0:3], v[210:213], v[184:187], v[0:3]
	v_mfma_f32_16x16x32_bf16 v[56:59], v[206:209], v[164:167], v[56:59]
	v_mfma_f32_16x16x32_bf16 v[48:51], v[214:217], v[164:167], v[48:51]
	v_mfma_f32_16x16x32_bf16 v[40:43], v[206:209], v[172:175], v[40:43]
	v_mfma_f32_16x16x32_bf16 v[32:35], v[214:217], v[172:175], v[32:35]
	v_mfma_f32_16x16x32_bf16 v[24:27], v[206:209], v[180:183], v[24:27]
	v_mfma_f32_16x16x32_bf16 v[16:19], v[214:217], v[180:183], v[16:19]
	v_mfma_f32_16x16x32_bf16 v[8:11], v[206:209], v[188:191], v[8:11]
	v_mfma_f32_16x16x32_bf16 v[0:3], v[214:217], v[188:191], v[0:3]
	s_add_i32 s40, s40, 2
	s_add_u32 s38, s38, 0x100
	s_addc_u32 s39, s39, 0
	s_add_u32 s18, s18, 0x100
	s_addc_u32 s19, s19, 0
	s_cmp_gt_u32 s40, 13
	s_barrier

.LBB0_2803:
	v_mov_b64_e32 v[0:1], 0x580
	s_ashr_i32 s9, s8, 31
	v_cmp_lt_i64_e32 vcc, s[12:13], v[0:1]
	s_lshl_b64 s[12:13], s[8:9], 19
	s_add_u32 s12, s82, s12
	s_addc_u32 s13, s83, s13
	s_and_b64 s[14:15], vcc, exec
	s_cselect_b32 s9, s13, s21
	s_cselect_b32 s33, s12, s20
	s_ashr_i32 s11, s10, 31
	s_lshl_b64 s[14:15], s[10:11], 19
	s_add_u32 s14, s26, s14
	s_addc_u32 s15, s27, s15
	s_and_b64 s[22:23], vcc, exec
	s_cselect_b32 s11, s15, s19
	s_cselect_b32 s38, s14, s18
	s_add_u32 s39, s18, 0x100
	s_addc_u32 s40, s19, 0
	s_add_u32 s18, s20, 0x40080
	s_addc_u32 s19, s21, 0
	s_mov_b32 s41, -2
	s_waitcnt vmcnt(0)
	v_add_u32_e32 v202, 0x10000, v151
	v_add_u32_e32 v203, 0x14000, v151
	v_add_u32_e32 v204, 0x18000, v151
	v_add_u32_e32 v205, 0x1c000, v151
	s_add_u32 s20, s18, 0xfffc0080
	s_addc_u32 s21, s19, -1
	s_add_i32 s42, 0, 0x10000
	ds_read_b128 v[138:141], v202
	ds_read_b128 v[142:145], v202 offset:1024
	ds_read_b128 v[146:149], v202 offset:2048
	ds_read_b128 v[154:157], v202 offset:3072
	s_cmp_eq_u32 s41, 12
	s_cselect_b32 s23, s9, s21
	s_cselect_b32 s22, s33, s20
	s_cselect_b32 s21, s11, s40
	s_cselect_b32 s20, s38, s39
	s_add_i32 m0, s17, 0xc000
	ds_read_b128 v[158:161], v152
	ds_read_b128 v[162:165], v152 offset:1024
	ds_read_b128 v[166:169], v152 offset:2048
	ds_read_b128 v[170:173], v152 offset:3072
	ds_read_b128 v[174:177], v152 offset:4096
	ds_read_b128 v[178:181], v152 offset:5120
	ds_read_b128 v[182:185], v152 offset:6144
	ds_read_b128 v[186:189], v152 offset:7168
	global_load_lds_dwordx4 v136, s[18:19]
	s_add_i32 m0, s17, 0xe000
	s_nop 0
	global_load_lds_dwordx4 v134, s[18:19]
	s_waitcnt lgkmcnt(8)
	s_barrier
	s_waitcnt lgkmcnt(0)
	v_mfma_f32_16x16x32_bf16 v[124:127], v[138:141], v[158:161], 0
	v_mfma_f32_16x16x32_bf16 v[116:119], v[146:149], v[158:161], 0
	v_mfma_f32_16x16x32_bf16 v[108:111], v[138:141], v[166:169], 0
	v_mfma_f32_16x16x32_bf16 v[100:103], v[146:149], v[166:169], 0
	v_mfma_f32_16x16x32_bf16 v[92:95], v[138:141], v[174:177], 0
	v_mfma_f32_16x16x32_bf16 v[84:87], v[146:149], v[174:177], 0
	v_mfma_f32_16x16x32_bf16 v[76:79], v[138:141], v[182:185], 0
	v_mfma_f32_16x16x32_bf16 v[68:71], v[146:149], v[182:185], 0
	v_mfma_f32_16x16x32_bf16 v[124:127], v[142:145], v[162:165], v[124:127]
	v_mfma_f32_16x16x32_bf16 v[116:119], v[154:157], v[162:165], v[116:119]
	v_mfma_f32_16x16x32_bf16 v[108:111], v[142:145], v[170:173], v[108:111]
	v_mfma_f32_16x16x32_bf16 v[100:103], v[154:157], v[170:173], v[100:103]
	v_mfma_f32_16x16x32_bf16 v[92:95], v[142:145], v[178:181], v[92:95]
	v_mfma_f32_16x16x32_bf16 v[84:87], v[154:157], v[178:181], v[84:87]
	v_mfma_f32_16x16x32_bf16 v[76:79], v[142:145], v[186:189], v[76:79]
	v_mfma_f32_16x16x32_bf16 v[68:71], v[154:157], v[186:189], v[68:71]
	s_barrier
	s_add_i32 s44, 0, 0x14000
	s_add_i32 s42, s42, s28
	s_mov_b32 m0, s42
	ds_read_b128 v[198:201], v203
	ds_read_b128 v[206:209], v203 offset:1024
	ds_read_b128 v[210:213], v203 offset:2048
	ds_read_b128 v[214:217], v203 offset:3072
	global_load_lds_dwordx4 v192, s[20:21]
	s_add_i32 m0, s42, 0x2000
	s_nop 0
	global_load_lds_dwordx4 v128, s[20:21]
	s_barrier
	s_waitcnt lgkmcnt(0)
	v_mfma_f32_16x16x32_bf16 v[120:123], v[198:201], v[158:161], 0
	v_mfma_f32_16x16x32_bf16 v[112:115], v[210:213], v[158:161], 0
	v_mfma_f32_16x16x32_bf16 v[104:107], v[198:201], v[166:169], 0
	v_mfma_f32_16x16x32_bf16 v[96:99], v[210:213], v[166:169], 0
	v_mfma_f32_16x16x32_bf16 v[88:91], v[198:201], v[174:177], 0
	v_mfma_f32_16x16x32_bf16 v[80:83], v[210:213], v[174:177], 0
	v_mfma_f32_16x16x32_bf16 v[72:75], v[198:201], v[182:185], 0
	v_mfma_f32_16x16x32_bf16 v[64:67], v[210:213], v[182:185], 0
	v_mfma_f32_16x16x32_bf16 v[120:123], v[206:209], v[162:165], v[120:123]
	v_mfma_f32_16x16x32_bf16 v[112:115], v[214:217], v[162:165], v[112:115]
	v_mfma_f32_16x16x32_bf16 v[104:107], v[206:209], v[170:173], v[104:107]
	v_mfma_f32_16x16x32_bf16 v[96:99], v[214:217], v[170:173], v[96:99]
	v_mfma_f32_16x16x32_bf16 v[88:91], v[206:209], v[178:181], v[88:91]
	v_mfma_f32_16x16x32_bf16 v[80:83], v[214:217], v[178:181], v[80:83]
	v_mfma_f32_16x16x32_bf16 v[72:75], v[206:209], v[186:189], v[72:75]
	v_mfma_f32_16x16x32_bf16 v[64:67], v[214:217], v[186:189], v[64:67]
	s_mov_b32 m0, s17
	s_add_u32 vcc_lo, s22, 0x80
	s_addc_u32 vcc_hi, s23, 0
	s_barrier
	ds_read_b128 v[158:161], v152 offset:16384
	ds_read_b128 v[162:165], v152 offset:17408
	ds_read_b128 v[166:169], v152 offset:18432
	ds_read_b128 v[170:173], v152 offset:19456
	ds_read_b128 v[174:177], v152 offset:20480
	ds_read_b128 v[178:181], v152 offset:21504
	ds_read_b128 v[182:185], v152 offset:22528
	ds_read_b128 v[186:189], v152 offset:23552
	global_load_lds_dwordx4 v132, s[22:23]
	s_mov_b32 m0, s29
	s_nop 0
	global_load_lds_dwordx4 v130, s[22:23]
	s_barrier
	s_waitcnt lgkmcnt(0)
	v_mfma_f32_16x16x32_bf16 v[60:63], v[138:141], v[158:161], 0
	v_mfma_f32_16x16x32_bf16 v[52:55], v[146:149], v[158:161], 0
	v_mfma_f32_16x16x32_bf16 v[44:47], v[138:141], v[166:169], 0
	v_mfma_f32_16x16x32_bf16 v[36:39], v[146:149], v[166:169], 0
	v_mfma_f32_16x16x32_bf16 v[28:31], v[138:141], v[174:177], 0
	v_mfma_f32_16x16x32_bf16 v[20:23], v[146:149], v[174:177], 0
	v_mfma_f32_16x16x32_bf16 v[12:15], v[138:141], v[182:185], 0
	v_mfma_f32_16x16x32_bf16 v[4:7], v[146:149], v[182:185], 0
	v_mfma_f32_16x16x32_bf16 v[60:63], v[142:145], v[162:165], v[60:63]
	v_mfma_f32_16x16x32_bf16 v[52:55], v[154:157], v[162:165], v[52:55]
	v_mfma_f32_16x16x32_bf16 v[44:47], v[142:145], v[170:173], v[44:47]
	v_mfma_f32_16x16x32_bf16 v[36:39], v[154:157], v[170:173], v[36:39]
	v_mfma_f32_16x16x32_bf16 v[28:31], v[142:145], v[178:181], v[28:31]
	v_mfma_f32_16x16x32_bf16 v[20:23], v[154:157], v[178:181], v[20:23]
	v_mfma_f32_16x16x32_bf16 v[12:15], v[142:145], v[186:189], v[12:15]
	v_mfma_f32_16x16x32_bf16 v[4:7], v[154:157], v[186:189], v[4:7]
	s_barrier
	s_add_u32 s42, s20, 0x40000
	s_addc_u32 s43, s21, 0
	s_add_i32 s44, s44, s28
	s_mov_b32 m0, s44
	s_nop 0
	global_load_lds_dwordx4 v192, s[42:43]
	s_add_i32 m0, s44, 0x2000
	s_nop 0
	global_load_lds_dwordx4 v128, s[42:43]
	s_waitcnt vmcnt(6)
	s_barrier
	v_mfma_f32_16x16x32_bf16 v[56:59], v[198:201], v[158:161], 0
	v_mfma_f32_16x16x32_bf16 v[48:51], v[210:213], v[158:161], 0
	v_mfma_f32_16x16x32_bf16 v[40:43], v[198:201], v[166:169], 0
	v_mfma_f32_16x16x32_bf16 v[32:35], v[210:213], v[166:169], 0
	v_mfma_f32_16x16x32_bf16 v[24:27], v[198:201], v[174:177], 0
	v_mfma_f32_16x16x32_bf16 v[16:19], v[210:213], v[174:177], 0
	v_mfma_f32_16x16x32_bf16 v[8:11], v[198:201], v[182:185], 0
	v_mfma_f32_16x16x32_bf16 v[0:3], v[210:213], v[182:185], 0
	v_mfma_f32_16x16x32_bf16 v[56:59], v[206:209], v[162:165], v[56:59]
	v_mfma_f32_16x16x32_bf16 v[48:51], v[214:217], v[162:165], v[48:51]
	v_mfma_f32_16x16x32_bf16 v[40:43], v[206:209], v[170:173], v[40:43]
	v_mfma_f32_16x16x32_bf16 v[32:35], v[214:217], v[170:173], v[32:35]
	v_mfma_f32_16x16x32_bf16 v[24:27], v[206:209], v[178:181], v[24:27]
	v_mfma_f32_16x16x32_bf16 v[16:19], v[214:217], v[178:181], v[16:19]
	v_mfma_f32_16x16x32_bf16 v[8:11], v[206:209], v[186:189], v[8:11]
	v_mfma_f32_16x16x32_bf16 v[0:3], v[214:217], v[186:189], v[0:3]
	s_add_i32 s42, 0, 0x18000
	s_barrier
	ds_read_b128 v[138:141], v204
	ds_read_b128 v[142:145], v204 offset:1024
	ds_read_b128 v[146:149], v204 offset:2048
	ds_read_b128 v[154:157], v204 offset:3072
	s_add_u32 s22, s22, 0x40000
	s_addc_u32 s23, s23, 0
	s_mov_b32 m0, s30
	ds_read_b128 v[158:161], v152 offset:32768
	ds_read_b128 v[162:165], v152 offset:33792
	ds_read_b128 v[166:169], v152 offset:34816
	ds_read_b128 v[170:173], v152 offset:35840
	ds_read_b128 v[174:177], v152 offset:36864
	ds_read_b128 v[178:181], v152 offset:37888
	ds_read_b128 v[182:185], v152 offset:38912
	ds_read_b128 v[186:189], v152 offset:39936
	global_load_lds_dwordx4 v132, s[22:23]
	s_mov_b32 m0, s31
	s_nop 0
	global_load_lds_dwordx4 v130, s[22:23]
	s_waitcnt lgkmcnt(8)
	s_barrier
	s_waitcnt lgkmcnt(0)
	v_mfma_f32_16x16x32_bf16 v[124:127], v[138:141], v[158:161], v[124:127]
	v_mfma_f32_16x16x32_bf16 v[116:119], v[146:149], v[158:161], v[116:119]
	v_mfma_f32_16x16x32_bf16 v[108:111], v[138:141], v[166:169], v[108:111]
	v_mfma_f32_16x16x32_bf16 v[100:103], v[146:149], v[166:169], v[100:103]
	v_mfma_f32_16x16x32_bf16 v[92:95], v[138:141], v[174:177], v[92:95]
	v_mfma_f32_16x16x32_bf16 v[84:87], v[146:149], v[174:177], v[84:87]
	v_mfma_f32_16x16x32_bf16 v[76:79], v[138:141], v[182:185], v[76:79]
	v_mfma_f32_16x16x32_bf16 v[68:71], v[146:149], v[182:185], v[68:71]
	v_mfma_f32_16x16x32_bf16 v[124:127], v[142:145], v[162:165], v[124:127]
	v_mfma_f32_16x16x32_bf16 v[116:119], v[154:157], v[162:165], v[116:119]
	v_mfma_f32_16x16x32_bf16 v[108:111], v[142:145], v[170:173], v[108:111]
	v_mfma_f32_16x16x32_bf16 v[100:103], v[154:157], v[170:173], v[100:103]
	v_mfma_f32_16x16x32_bf16 v[92:95], v[142:145], v[178:181], v[92:95]
	v_mfma_f32_16x16x32_bf16 v[84:87], v[154:157], v[178:181], v[84:87]
	v_mfma_f32_16x16x32_bf16 v[76:79], v[142:145], v[186:189], v[76:79]
	v_mfma_f32_16x16x32_bf16 v[68:71], v[154:157], v[186:189], v[68:71]
	s_barrier
	s_add_i32 s22, 0, 0x1c000
	s_add_i32 s23, s42, s28
	s_add_u32 s100, s20, 0x80
	s_addc_u32 s101, s21, 0
	s_mov_b32 m0, s23
	ds_read_b128 v[198:201], v205
	ds_read_b128 v[206:209], v205 offset:1024
	ds_read_b128 v[210:213], v205 offset:2048
	ds_read_b128 v[214:217], v205 offset:3072
	global_load_lds_dwordx4 v192, s[100:101]
	s_add_i32 m0, s23, 0x2000
	s_nop 0
	global_load_lds_dwordx4 v128, s[100:101]
	s_barrier
	s_waitcnt lgkmcnt(0)
	v_mfma_f32_16x16x32_bf16 v[120:123], v[198:201], v[158:161], v[120:123]
	v_mfma_f32_16x16x32_bf16 v[112:115], v[210:213], v[158:161], v[112:115]
	v_mfma_f32_16x16x32_bf16 v[104:107], v[198:201], v[166:169], v[104:107]
	v_mfma_f32_16x16x32_bf16 v[96:99], v[210:213], v[166:169], v[96:99]
	v_mfma_f32_16x16x32_bf16 v[88:91], v[198:201], v[174:177], v[88:91]
	v_mfma_f32_16x16x32_bf16 v[80:83], v[210:213], v[174:177], v[80:83]
	v_mfma_f32_16x16x32_bf16 v[72:75], v[198:201], v[182:185], v[72:75]
	v_mfma_f32_16x16x32_bf16 v[64:67], v[210:213], v[182:185], v[64:67]
	v_mfma_f32_16x16x32_bf16 v[120:123], v[206:209], v[162:165], v[120:123]
	v_mfma_f32_16x16x32_bf16 v[112:115], v[214:217], v[162:165], v[112:115]
	v_mfma_f32_16x16x32_bf16 v[104:107], v[206:209], v[170:173], v[104:107]
	v_mfma_f32_16x16x32_bf16 v[96:99], v[214:217], v[170:173], v[96:99]
	v_mfma_f32_16x16x32_bf16 v[88:91], v[206:209], v[178:181], v[88:91]
	v_mfma_f32_16x16x32_bf16 v[80:83], v[214:217], v[178:181], v[80:83]
	v_mfma_f32_16x16x32_bf16 v[72:75], v[206:209], v[186:189], v[72:75]
	v_mfma_f32_16x16x32_bf16 v[64:67], v[214:217], v[186:189], v[64:67]
	s_mov_b32 m0, s34
	s_barrier
	ds_read_b128 v[158:161], v152 offset:49152
	ds_read_b128 v[162:165], v152 offset:50176
	ds_read_b128 v[166:169], v152 offset:51200
	ds_read_b128 v[170:173], v152 offset:52224
	ds_read_b128 v[174:177], v152 offset:53248
	ds_read_b128 v[178:181], v152 offset:54272
	ds_read_b128 v[182:185], v152 offset:55296
	ds_read_b128 v[186:189], v152 offset:56320
	global_load_lds_dwordx4 v132, vcc
	s_mov_b32 m0, s35
	s_nop 0
	global_load_lds_dwordx4 v130, vcc
	s_barrier
	s_waitcnt lgkmcnt(0)
	v_mfma_f32_16x16x32_bf16 v[60:63], v[138:141], v[158:161], v[60:63]
	v_mfma_f32_16x16x32_bf16 v[52:55], v[146:149], v[158:161], v[52:55]
	v_mfma_f32_16x16x32_bf16 v[44:47], v[138:141], v[166:169], v[44:47]
	v_mfma_f32_16x16x32_bf16 v[36:39], v[146:149], v[166:169], v[36:39]
	v_mfma_f32_16x16x32_bf16 v[28:31], v[138:141], v[174:177], v[28:31]
	v_mfma_f32_16x16x32_bf16 v[20:23], v[146:149], v[174:177], v[20:23]
	v_mfma_f32_16x16x32_bf16 v[12:15], v[138:141], v[182:185], v[12:15]
	v_mfma_f32_16x16x32_bf16 v[4:7], v[146:149], v[182:185], v[4:7]
	v_mfma_f32_16x16x32_bf16 v[60:63], v[142:145], v[162:165], v[60:63]
	v_mfma_f32_16x16x32_bf16 v[52:55], v[154:157], v[162:165], v[52:55]
	v_mfma_f32_16x16x32_bf16 v[44:47], v[142:145], v[170:173], v[44:47]
	v_mfma_f32_16x16x32_bf16 v[36:39], v[154:157], v[170:173], v[36:39]
	v_mfma_f32_16x16x32_bf16 v[28:31], v[142:145], v[178:181], v[28:31]
	v_mfma_f32_16x16x32_bf16 v[20:23], v[154:157], v[178:181], v[20:23]
	v_mfma_f32_16x16x32_bf16 v[12:15], v[142:145], v[186:189], v[12:15]
	v_mfma_f32_16x16x32_bf16 v[4:7], v[154:157], v[186:189], v[4:7]
	s_barrier
	s_add_u32 s20, s20, 0x40080
	s_addc_u32 s21, s21, 0
	s_add_i32 s22, s22, s28
	s_mov_b32 m0, s22
	s_nop 0
	global_load_lds_dwordx4 v192, s[20:21]
	s_add_i32 m0, s22, 0x2000
	s_nop 0
	global_load_lds_dwordx4 v128, s[20:21]
	s_waitcnt vmcnt(6)
	s_barrier
	v_mfma_f32_16x16x32_bf16 v[56:59], v[198:201], v[158:161], v[56:59]
	v_mfma_f32_16x16x32_bf16 v[48:51], v[210:213], v[158:161], v[48:51]
	v_mfma_f32_16x16x32_bf16 v[40:43], v[198:201], v[166:169], v[40:43]
	v_mfma_f32_16x16x32_bf16 v[32:35], v[210:213], v[166:169], v[32:35]
	v_mfma_f32_16x16x32_bf16 v[24:27], v[198:201], v[174:177], v[24:27]
	v_mfma_f32_16x16x32_bf16 v[16:19], v[210:213], v[174:177], v[16:19]
	v_mfma_f32_16x16x32_bf16 v[8:11], v[198:201], v[182:185], v[8:11]
	v_mfma_f32_16x16x32_bf16 v[0:3], v[210:213], v[182:185], v[0:3]
	v_mfma_f32_16x16x32_bf16 v[56:59], v[206:209], v[162:165], v[56:59]
	v_mfma_f32_16x16x32_bf16 v[48:51], v[214:217], v[162:165], v[48:51]
	v_mfma_f32_16x16x32_bf16 v[40:43], v[206:209], v[170:173], v[40:43]
	v_mfma_f32_16x16x32_bf16 v[32:35], v[214:217], v[170:173], v[32:35]
	v_mfma_f32_16x16x32_bf16 v[24:27], v[206:209], v[178:181], v[24:27]
	v_mfma_f32_16x16x32_bf16 v[16:19], v[214:217], v[178:181], v[16:19]
	v_mfma_f32_16x16x32_bf16 v[8:11], v[206:209], v[186:189], v[8:11]
	v_mfma_f32_16x16x32_bf16 v[0:3], v[214:217], v[186:189], v[0:3]
	s_add_i32 s41, s41, 2
	s_add_u32 s39, s39, 0x100
	s_addc_u32 s40, s40, 0
	s_add_u32 s18, s18, 0x100
	s_addc_u32 s19, s19, 0
	s_cmp_gt_u32 s41, 13
	s_barrier
